# latent diff-attention: K/V prefetch addresses as running 64-bit pointers (strength-reduced from 4 64-bit mads + selects per block)
# baseline (speedup 1.0000x reference)
; template <int KW, int DV, bool NA> ...
;     constexpr int KSTR = KW * 2 + 16, VSTR = DV * 2 + 64, KCH = KW / 8, VCH = DV / 8, NK = KW / 64, NV = DV / 64;
;     constexpr int STAGE = 64 * KSTR + 64 * VSTR;
;     const int tid = otid(), lane = tid & 63, q32 = lane & 31, hi = lane >> 5;
;     const bool gB = (tid >> 8) != 0;
;     u32x4 kA[NK], vA[NV], kB[NK], vB[NV];
;     auto rowbase = [&](int i) -> size_t { return i < n1 ? base1 + (size_t)64 * i : base2 + (size_t)64 * (i - n1); };
;     auto prefetch = [&](int i, u32x4 (&kreg)[NK], u32x4 (&vreg)[NV]) {
;         const size_t rb = rowbase(i);
; #pragma unroll
;         for (int e = 0; e < NK; ++e) { const int c = tid + 512 * e; kreg[e] = *(const u32x4*)(Kg + (rb + c / KCH) * pitch + (c % KCH) * 8); }
; #pragma unroll
;         for (int e = 0; e < NV; ++e) { const int c = tid + 512 * e; vreg[e] = *(const u32x4*)(Vg + (rb + c / VCH) * pitch + (c % VCH) * 8); }
;     };
;     auto stash = [&](int st, const u32x4 (&kreg)[NK], const u32x4 (&vreg)[NV]) {
;         unsigned char* Kt = lds + st * STAGE; unsigned char* Vt = Kt + 64 * KSTR;
; #pragma unroll
;         for (int e = 0; e < NK; ++e) { const int c = tid + 512 * e; *(u32x4*)(Kt + (c / KCH) * KSTR + (c % KCH) * 16) = kreg[e]; }
; #pragma unroll
;         for (int e = 0; e < NV; ++e) { const int c = tid + 512 * e; *(u32x4*)(Vt + (c / VCH) * VSTR + (c % VCH) * 16) = vreg[e]; }
;     };
;     float m_ref = 0.f, l_run = 0.f; bool first = true;
;     u32x4 pw[4];
;     f32x16 negm = {}; asm volatile("" : "+v"(negm));
; #pragma unroll
; __device__ __forceinline__ void diff_unit(const Params& p, int l, int b, int h, size_t qrow0, int tile_lo, unsigned char* lds) {
;     const int tid = otid(), wave = tid >> 6, lane = tid & 63, q32 = lane & 31, hi = lane >> 5, qg = wave >> 1, m = wave & 1;
;     const bf16_t* dfq = (const bf16_t*)(p.ws + WS_DFQ); bf16_t* gout = (bf16_t*)(p.ws + WS_G3) + (size_t)2 * T * 512;
;     const size_t qrow = qrow0 + qg * 32 + q32;
;     bf16x8 qf[4];
; #pragma unroll
;     for (int d0 = 0; d0 < 4; ++d0) qf[d0] = *(const bf16x8*)(dfq + qrow * 1536 + h * 128 + m * 64 + 16 * d0 + 8 * hi);
;     f32x16 o[4]; float lsum;
;     const int n1 = 64 - tile_lo;
;     attn_loop<128, 128, false>(lds, dfq + 512 + h * 128, dfq + 1024 + h * 128, 1536, n1, (size_t)b * SEQ, n1 + 4, (size_t)TL + b * CTXL,
.LBB0_589:
	s_andn2_saveexec_b64 s[42:43], s[22:23]
	s_cbranch_execz .LBB0_360
	v_ashrrev_i32_e32 v0, 2, v54
	v_and_or_b32 v0, v0, -8, s31
	v_ashrrev_i32_e32 v34, 2, v0
	v_ashrrev_i32_e32 v35, 31, v34
	v_lshlrev_b64 v[166:167], 12, v[34:35]
	v_mov_b32_e32 v35, v237
	v_lshlrev_b32_e32 v0, 7, v54
	v_and_b32_e32 v0, 0xf80, v0
	v_ashrrev_i32_e32 v186, 7, v35
	v_and_b32_e32 v184, 31, v35
	v_lshlrev_b32_e32 v2, 5, v186
	v_ashrrev_i32_e32 v3, 31, v2
	v_or3_b32 v4, v184, v0, v166
	v_mov_b32_e32 v5, v167
	v_lshl_add_u64 v[164:165], v[4:5], 0, v[2:3]
	v_mov_b64_e32 v[2:3], s[52:53]
	v_bfe_u32 v185, v35, 6, 1
	v_mad_u64_u32 v[2:3], s[0:1], v164, s33, v[2:3]
	v_bfe_u32 v183, v35, 5, 1
	v_mad_i32_i24 v3, v165, s33, v3
	v_lshlrev_b32_e32 v0, 7, v185
	v_lshl_add_u64 v[2:3], v[2:3], 0, v[0:1]
	v_lshlrev_b32_e32 v162, 4, v183
	v_mov_b32_e32 v163, v1
	v_lshl_add_u64 v[2:3], v[2:3], 0, v[162:163]
	v_mov_b32_e32 v52, v237
	global_load_dwordx4 v[114:117], v[2:3], off
	global_load_dwordx4 v[118:121], v[2:3], off offset:32
	global_load_dwordx4 v[122:125], v[2:3], off offset:64
	global_load_dwordx4 v[126:129], v[2:3], off offset:96
	v_mov_b64_e32 v[42:43], s[56:57]
	v_ashrrev_i32_e32 v18, 31, v52
	v_lshrrev_b32_e32 v18, 28, v18
	v_add_u32_e32 v20, v52, v18
	v_ashrrev_i32_e32 v168, 4, v20
	v_and_b32_e32 v20, -16, v20
	v_sub_u32_e32 v53, v52, v20
	v_lshlrev_b32_e32 v20, 3, v53
	v_ashrrev_i32_e32 v21, 31, v20
	v_add_u32_e32 v22, 0x200, v52
	v_lshlrev_b64 v[38:39], 1, v[20:21]
	v_ashrrev_i32_e32 v20, 31, v22
	v_lshrrev_b32_e32 v20, 28, v20
	v_ashrrev_i32_e32 v169, 31, v168
	v_add_u32_e32 v23, v22, v20
	v_lshl_add_u64 v[26:27], v[166:167], 0, v[168:169]
	v_ashrrev_i32_e32 v170, 4, v23
	v_and_b32_e32 v23, -16, v23
	v_mov_b64_e32 v[36:37], s[54:55]
	v_ashrrev_i32_e32 v171, 31, v170
	v_sub_u32_e32 v54, v22, v23
	v_mad_u64_u32 v[30:31], s[0:1], v26, s33, v[42:43]
	v_or_b32_e32 v44, 64, v166
	v_mov_b32_e32 v45, v167
	v_mad_u64_u32 v[18:19], s[0:1], v26, s33, v[36:37]
	v_lshl_add_u64 v[28:29], v[166:167], 0, v[170:171]
	v_lshlrev_b32_e32 v22, 3, v54
	v_mad_i32_i24 v31, v27, s33, v31
	v_lshl_add_u64 v[46:47], v[44:45], 0, v[168:169]
	v_mov_b32_e32 v16, v1
	v_mov_b32_e32 v17, v1
	v_mad_i32_i24 v19, v27, s33, v19
	v_mad_u64_u32 v[20:21], s[0:1], v28, s33, v[36:37]
	v_ashrrev_i32_e32 v23, 31, v22
	v_lshl_add_u64 v[26:27], v[30:31], 0, v[38:39]
	v_mad_u64_u32 v[30:31], s[0:1], v28, s33, v[42:43]
	v_mad_u64_u32 v[48:49], s[0:1], v46, s33, v[36:37]
	v_lshl_add_u64 v[44:45], v[44:45], 0, v[170:171]
	v_mov_b32_e32 v2, v1
	v_mov_b32_e32 v3, v1
	v_mov_b32_e32 v4, v1
	v_mov_b32_e32 v5, v1
	v_mov_b32_e32 v6, v1
	v_mov_b32_e32 v7, v1
	v_mov_b32_e32 v8, v1
	v_mov_b32_e32 v9, v1
	v_mov_b32_e32 v10, v1
	v_mov_b32_e32 v11, v1
	v_mov_b32_e32 v12, v1
	v_mov_b32_e32 v13, v1
	v_mov_b32_e32 v14, v1
	v_mov_b32_e32 v15, v1
	v_mov_b64_e32 v[80:81], v[16:17]
	v_mad_i32_i24 v21, v29, s33, v21
	v_lshlrev_b64 v[40:41], 1, v[22:23]
	v_mad_i32_i24 v31, v29, s33, v31
	v_mad_i32_i24 v49, v47, s33, v49
	v_mad_u64_u32 v[50:51], s[0:1], v44, s33, v[36:37]
	v_mov_b64_e32 v[78:79], v[14:15]
	v_mov_b64_e32 v[76:77], v[12:13]
	v_mov_b64_e32 v[74:75], v[10:11]
	v_mov_b64_e32 v[72:73], v[8:9]
	v_mov_b64_e32 v[70:71], v[6:7]
	v_mov_b64_e32 v[68:69], v[4:5]
	v_mov_b64_e32 v[66:67], v[2:3]
	v_lshl_add_u64 v[18:19], v[18:19], 0, v[38:39]
	v_lshl_add_u64 v[22:23], v[20:21], 0, v[40:41]
	v_lshl_add_u64 v[30:31], v[30:31], 0, v[40:41]
	v_lshl_add_u64 v[48:49], v[48:49], 0, v[38:39]
	v_mad_i32_i24 v51, v45, s33, v51
	global_load_dwordx4 v[18:21], v[18:19], off
	s_nop 0
	global_load_dwordx4 v[22:25], v[22:23], off
	s_nop 0
	global_load_dwordx4 v[26:29], v[26:27], off
	s_nop 0
	global_load_dwordx4 v[30:33], v[30:31], off
	v_lshl_add_u64 v[50:51], v[50:51], 0, v[40:41]
	global_load_dwordx4 v[130:133], v[48:49], off
	global_load_dwordx4 v[134:137], v[50:51], off
	v_mad_u64_u32 v[48:49], s[0:1], v46, s33, v[42:43]
	v_mad_i32_i24 v49, v47, s33, v49
	v_lshl_add_u64 v[46:47], v[48:49], 0, v[38:39]
	v_mad_u64_u32 v[48:49], s[0:1], v44, s33, v[42:43]
	v_mad_i32_i24 v49, v45, s33, v49
	v_lshl_add_u64 v[44:45], v[48:49], 0, v[40:41]
	global_load_dwordx4 v[138:141], v[46:47], off
	global_load_dwordx4 v[142:145], v[44:45], off
	v_or_b32_e32 v44, 0x80, v166
	v_mov_b32_e32 v45, v167
	v_lshl_add_u64 v[46:47], v[44:45], 0, v[168:169]
	v_lshl_add_u64 v[44:45], v[44:45], 0, v[170:171]
	v_mad_u64_u32 v[48:49], s[0:1], v46, s33, v[36:37]
	v_mad_u64_u32 v[36:37], s[0:1], v44, s33, v[36:37]
	v_mad_i32_i24 v49, v47, s33, v49
	v_mad_i32_i24 v37, v45, s33, v37
	v_lshl_add_u64 v[48:49], v[48:49], 0, v[38:39]
	v_lshl_add_u64 v[36:37], v[36:37], 0, v[40:41]
	global_load_dwordx4 v[146:149], v[48:49], off
	global_load_dwordx4 v[150:153], v[36:37], off
	v_mad_u64_u32 v[36:37], s[0:1], v46, s33, v[42:43]
	v_mad_i32_i24 v37, v47, s33, v37
	v_mad_u64_u32 v[42:43], s[0:1], v44, s33, v[42:43]
	v_lshl_add_u64 v[36:37], v[36:37], 0, v[38:39]
	v_mad_i32_i24 v43, v45, s33, v43
	v_lshl_add_u64 v[42:43], v[42:43], 0, v[40:41]
	global_load_dwordx4 v[154:157], v[36:37], off
	global_load_dwordx4 v[158:161], v[42:43], off
	v_lshlrev_b32_e32 v34, 8, v34
	v_and_b32_e32 v163, 63, v35
	v_ashrrev_i32_e32 v35, 31, v34
	s_mov_b64 s[0:1], 0x8000
	v_mul_lo_u32 v187, v168, s24
	v_lshlrev_b32_e32 v188, 4, v53
	v_lshl_add_u64 v[172:173], v[34:35], 0, s[0:1]
	v_bfe_u32 v36, v52, 5, 1
	v_add3_u32 v34, 0, v187, v188
	v_mul_lo_u32 v189, v170, s24
	v_lshlrev_b32_e32 v190, 4, v54
	v_and_b32_e32 v35, 31, v52
	v_lshl_or_b32 v194, v36, 4, v0
	v_bfe_u32 v0, v52, 2, 2
	v_lshl_or_b32 v0, v36, 2, v0
	v_mul_u32_u24_e32 v195, 0x140, v0
	v_and_b32_e32 v0, 16, v52
	v_lshl_add_u64 v[174:175], s[54:55], 0, v[38:39]
	v_lshl_add_u64 v[176:177], s[54:55], 0, v[40:41]
	v_lshl_add_u64 v[178:179], s[56:57], 0, v[38:39]
	v_lshl_add_u64 v[180:181], s[56:57], 0, v[40:41]
	v_mul_u32_u24_e32 v193, 0x110, v35
	s_mov_b32 s2, 2
	s_mov_b32 s8, 4
	s_mov_b32 s9, 0
	s_mov_b32 s10, 1
	v_mul_lo_u32 v191, v168, s83
	v_mul_lo_u32 v192, v170, s83
	v_mov_b32_e32 v196, 0
	v_mov_b32_e32 v197, 0
	s_waitcnt vmcnt(11)
; template <int KW, int DV, bool NA> ...
;     ...
;     auto prefetch = [&](int i, u32x4 (&kreg)[NK], u32x4 (&vreg)[NV]) {
;         const size_t rb = rowbase(i);
; #pragma unroll
;         for (int e = 0; e < NK; ++e) { const int c = tid + 512 * e; kreg[e] = *(const u32x4*)(Kg + (rb + c / KCH) * pitch + (c % KCH) * 8); }
; #pragma unroll
;         for (int e = 0; e < NV; ++e) { const int c = tid + 512 * e; vreg[e] = *(const u32x4*)(Vg + (rb + c / VCH) * pitch + (c % VCH) * 8); }
;     };
;     ...
;     prefetch(0, kA, vA); stash(0, kA, vA);
;     if (ntile > 1) prefetch(1, kB, vB);
;     if (ntile > 2) prefetch(2, kA, vA);
;     __syncthreads();
;     int st_cur = 0, st_prev = 2, st_next = 1;
;     auto step = [&](int i, u32x4 (&kreg)[NK], u32x4 (&vreg)[NV]) {
;         if (i + 1 < ntile) { stash(st_next, kreg, vreg); if (i + 3 < ntile) prefetch(i + 3, kreg, vreg); }
;         const unsigned char* Kt = lds + st_cur * STAGE;
;         if (is_active(i)) tile(i, Kt, Kt + 64 * KSTR);
;         __syncthreads();
;         const int t_ = st_prev; st_prev = st_cur; st_cur = st_next; st_next = t_;
;     };
; #pragma unroll 1
;     for (int i = 0; i < ntile; i += 2) { step(i, kB, vB); if (i + 1 < ntile) step(i + 1, kA, vA); }
	ds_write_b128 v34, v[18:21]
	v_add3_u32 v18, 0, v189, v190
	s_waitcnt vmcnt(10)
	ds_write_b128 v18, v[22:25]
	v_mad_u64_u32 v[20:21], s[0:1], v168, 48, v[34:35]
	v_mad_u64_u32 v[18:19], s[0:1], v170, 48, v[18:19]
	s_waitcnt vmcnt(9)
	ds_write_b128 v20, v[26:29] offset:17408
	s_waitcnt vmcnt(8)
	ds_write_b128 v18, v[30:33] offset:17408
	v_lshlrev_b32_e32 v18, 2, v52
	v_and_or_b32 v0, v18, 12, v0
	v_mov_b64_e32 v[32:33], v[16:17]
	v_mov_b64_e32 v[48:49], v[16:17]
	v_mov_b64_e32 v[64:65], v[16:17]
	v_lshlrev_b32_e32 v0, 1, v0
	s_mov_b64 s[0:1], -1
	v_mov_b64_e32 v[30:31], v[14:15]
	v_mov_b64_e32 v[28:29], v[12:13]
	v_mov_b64_e32 v[26:27], v[10:11]
	v_mov_b64_e32 v[24:25], v[8:9]
	v_mov_b64_e32 v[22:23], v[6:7]
	v_mov_b64_e32 v[20:21], v[4:5]
	v_mov_b64_e32 v[18:19], v[2:3]
	v_mov_b64_e32 v[46:47], v[14:15]
	v_mov_b64_e32 v[44:45], v[12:13]
	v_mov_b64_e32 v[42:43], v[10:11]
	v_mov_b64_e32 v[40:41], v[8:9]
	v_mov_b64_e32 v[38:39], v[6:7]
	v_mov_b64_e32 v[36:37], v[4:5]
	v_mov_b64_e32 v[34:35], v[2:3]
	v_mov_b64_e32 v[62:63], v[14:15]
	v_mov_b64_e32 v[60:61], v[12:13]
	v_mov_b64_e32 v[58:59], v[10:11]
	v_mov_b64_e32 v[56:57], v[8:9]
	v_mov_b64_e32 v[54:55], v[6:7]
	v_mov_b64_e32 v[52:53], v[4:5]
	v_mov_b64_e32 v[50:51], v[2:3]
	s_waitcnt lgkmcnt(0)
	s_barrier
	s_movk_i32 s4, 0xc0
	s_mov_b32 s5, 0
	v_lshl_add_u64 v[82:83], s[4:5], 0, v[166:167]
	v_lshl_add_u64 v[84:85], v[82:83], 0, v[168:169]
	v_lshl_add_u64 v[82:83], v[82:83], 0, v[170:171]
	v_mad_u64_u32 v[86:87], s[4:5], v84, s33, v[174:175]
	v_mad_i32_i24 v87, v85, s33, v87
	v_mad_u64_u32 v[88:89], s[4:5], v82, s33, v[176:177]
	v_mad_i32_i24 v89, v83, s33, v89
	v_mad_u64_u32 v[98:99], s[4:5], v84, s33, v[178:179]
	v_mad_i32_i24 v99, v85, s33, v99
	v_mad_u64_u32 v[100:101], s[4:5], v82, s33, v[180:181]
	v_mad_i32_i24 v101, v83, s33, v101
	v_mov_b64_e32 v[174:175], v[86:87]
	v_mov_b64_e32 v[176:177], v[88:89]
	v_mov_b64_e32 v[178:179], v[98:99]
	v_mov_b64_e32 v[180:181], v[100:101]
	v_sub_u32_e32 v82, v172, v166
	s_lshl_b32 s101, s33, 6
	v_readfirstlane_b32 s100, v82
	s_sub_i32 s100, s100, 0xfc0
	s_mul_i32 s100, s100, s33
.LBB0_591:
	s_mov_b32 s11, s2
	s_mul_i32 s2, s10, 0x9400
	s_add_i32 s13, s2, 0
	v_add3_u32 v82, s13, v187, v188
	s_waitcnt vmcnt(0)
	ds_write_b128 v82, v[130:133]
	v_add3_u32 v82, s13, v189, v190
	s_add_i32 s12, s8, -4
	ds_write_b128 v82, v[134:137]
	v_add3_u32 v82, s13, v191, v188
	ds_write_b128 v82, v[138:141] offset:17408
	v_add3_u32 v82, s13, v192, v190
	s_cmp_gt_u32 s12, 64
	ds_write_b128 v82, v[142:145] offset:17408
	s_cbranch_scc1 .LBB0_593
	global_load_dwordx4 v[130:133], v[174:175], off
	global_load_dwordx4 v[134:137], v[176:177], off
	global_load_dwordx4 v[138:141], v[178:179], off
	global_load_dwordx4 v[142:145], v[180:181], off
	s_cmp_eq_u32 s8, 64
	s_cselect_b32 s4, s100, s101
	s_mov_b32 s5, 0
	v_lshl_add_u64 v[174:175], s[4:5], 0, v[174:175]
	v_lshl_add_u64 v[176:177], s[4:5], 0, v[176:177]
	v_lshl_add_u64 v[178:179], s[4:5], 0, v[178:179]
	v_lshl_add_u64 v[180:181], s[4:5], 0, v[180:181]

; template <int KW, int DV, bool NA> ...
;     ...
;     auto prefetch = [&](int i, u32x4 (&kreg)[NK], u32x4 (&vreg)[NV]) {
;         const size_t rb = rowbase(i);
; #pragma unroll
;         for (int e = 0; e < NK; ++e) { const int c = tid + 512 * e; kreg[e] = *(const u32x4*)(Kg + (rb + c / KCH) * pitch + (c % KCH) * 8); }
; #pragma unroll
;         for (int e = 0; e < NV; ++e) { const int c = tid + 512 * e; vreg[e] = *(const u32x4*)(Vg + (rb + c / VCH) * pitch + (c % VCH) * 8); }
;     };
;     ...
;         const unsigned vb = (unsigned)(uintptr_t)(Vt + (4 * hi + ((lane & 15) >> 2)) * VSTR + (16 * ((lane >> 4) & 1) + 4 * (lane & 3)) * 2);
;         s16x4 lo[DT], hh[DT];
;     ...
; #pragma unroll
;         for (int d = 0; d < DT; ++d) TR_ISSUE(0, d);
;         float ps = 0.f;
;         SM_SLICE(p0, 0, 8); pw[0] = PACK8(p0, 0);
; #pragma unroll
;         for (int d = 0; d < DT; ++d) {
;             LGKM_WAIT(2 * (DT - 1));
;             o[d] = __builtin_amdgcn_mfma_f32_32x32x16_bf16(PV_VF(d), __builtin_bit_cast(bf16x8, pw[0]), o[d], 0, 0, 0);
;             TR_ISSUE(1, d);
;             SM_SLICE(p0, 8 + d * (8 / DT), 8 + (d + 1) * (8 / DT));
;             __builtin_amdgcn_sched_barrier(0);
;         }
;         pw[1] = PACK8(p0, 8);
; #pragma unroll
;         for (int d = 0; d < DT; ++d) {
;             LGKM_WAIT(2 * (DT - 1));
;             o[d] = __builtin_amdgcn_mfma_f32_32x32x16_bf16(PV_VF(d), __builtin_bit_cast(bf16x8, pw[1]), o[d], 0, 0, 0);
;             TR_ISSUE(2, d);
;             SM_SLICE(p1, d * (8 / DT), (d + 1) * (8 / DT));
;             __builtin_amdgcn_sched_barrier(0);
;         }
;         pw[2] = PACK8(p1, 0);
; #pragma unroll
;         for (int d = 0; d < DT; ++d) {
;             LGKM_WAIT(2 * (DT - 1));
;             o[d] = __builtin_amdgcn_mfma_f32_32x32x16_bf16(PV_VF(d), __builtin_bit_cast(bf16x8, pw[2]), o[d], 0, 0, 0);
;             TR_ISSUE(3, d);
;             SM_SLICE(p1, 8 + d * (8 / DT), 8 + (d + 1) * (8 / DT));
;             __builtin_amdgcn_sched_barrier(0);
;         }
;         pw[3] = PACK8(p1, 8);
;         l_run += ps;
;         asm volatile("s_waitcnt lgkmcnt(0)" ::: "memory"); __builtin_amdgcn_sched_barrier(0);
; #pragma unroll
;         for (int d = 0; d < DT; ++d) o[d] = __builtin_amdgcn_mfma_f32_32x32x16_bf16(PV_VF(d), __builtin_bit_cast(bf16x8, pw[3]), o[d], 0, 0, 0);
.LBB0_599:
	v_add_u32_e32 v198, s2, v195
	v_add3_u32 v204, v198, v0, s90
	ds_read_b64_tr_b16 v[198:199], v204 offset:0
	ds_read_b64_tr_b16 v[200:201], v204 offset:2560
	ds_read_b64_tr_b16 v[206:207], v204 offset:64
	ds_read_b64_tr_b16 v[208:209], v204 offset:2624
	ds_read_b64_tr_b16 v[210:211], v204 offset:128
	ds_read_b64_tr_b16 v[212:213], v204 offset:2688
	ds_read_b64_tr_b16 v[214:215], v204 offset:192
	ds_read_b64_tr_b16 v[216:217], v204 offset:2752
	v_exp_f32_e32 v98, v98
	v_exp_f32_e32 v99, v99
	v_exp_f32_e32 v100, v100
	v_exp_f32_e32 v101, v101
	v_exp_f32_e32 v102, v102
	v_exp_f32_e32 v103, v103
	v_exp_f32_e32 v104, v104
	v_exp_f32_e32 v105, v105
	s_waitcnt lgkmcnt(6)
	v_cvt_pk_bf16_f32 v218, v98, v99
	v_cvt_pk_bf16_f32 v219, v100, v101
	v_cvt_pk_bf16_f32 v220, v102, v103
	v_cvt_pk_bf16_f32 v221, v104, v105
	s_nop 1
	v_mfma_f32_32x32x16_bf16 v[50:65], v[198:201], v[218:221], v[50:65]
	ds_read_b64_tr_b16 v[198:199], v204 offset:5120
	v_exp_f32_e32 v106, v106
	v_exp_f32_e32 v107, v107
	ds_read_b64_tr_b16 v[200:201], v204 offset:7680
	s_waitcnt lgkmcnt(6)
	v_mfma_f32_32x32x16_bf16 v[34:49], v[206:209], v[218:221], v[34:49]
	ds_read_b64_tr_b16 v[206:207], v204 offset:5184
	v_exp_f32_e32 v108, v108
	v_exp_f32_e32 v109, v109
	ds_read_b64_tr_b16 v[208:209], v204 offset:7744
	s_waitcnt lgkmcnt(6)
	v_mfma_f32_32x32x16_bf16 v[18:33], v[210:213], v[218:221], v[18:33]
	ds_read_b64_tr_b16 v[210:211], v204 offset:5248
	v_exp_f32_e32 v110, v110
	v_exp_f32_e32 v111, v111
	ds_read_b64_tr_b16 v[212:213], v204 offset:7808
	s_waitcnt lgkmcnt(6)
	v_mfma_f32_32x32x16_bf16 v[2:17], v[214:217], v[218:221], v[2:17]
	ds_read_b64_tr_b16 v[214:215], v204 offset:5312
	v_exp_f32_e32 v112, v112
	v_exp_f32_e32 v113, v113
	ds_read_b64_tr_b16 v[216:217], v204 offset:7872
	s_waitcnt lgkmcnt(6)
	v_cvt_pk_bf16_f32 v218, v106, v107
	v_cvt_pk_bf16_f32 v219, v108, v109
	v_cvt_pk_bf16_f32 v220, v110, v111
	v_cvt_pk_bf16_f32 v221, v112, v113
	s_nop 1
	v_mfma_f32_32x32x16_bf16 v[50:65], v[198:201], v[218:221], v[50:65]
	ds_read_b64_tr_b16 v[198:199], v204 offset:10240
	v_exp_f32_e32 v82, v82
	v_exp_f32_e32 v83, v83
	ds_read_b64_tr_b16 v[200:201], v204 offset:12800
	s_waitcnt lgkmcnt(6)
	v_mfma_f32_32x32x16_bf16 v[34:49], v[206:209], v[218:221], v[34:49]
	ds_read_b64_tr_b16 v[206:207], v204 offset:10304
	v_exp_f32_e32 v84, v84
	v_exp_f32_e32 v85, v85
	ds_read_b64_tr_b16 v[208:209], v204 offset:12864
	s_waitcnt lgkmcnt(6)
	v_mfma_f32_32x32x16_bf16 v[18:33], v[210:213], v[218:221], v[18:33]
	ds_read_b64_tr_b16 v[210:211], v204 offset:10368
	v_exp_f32_e32 v86, v86
	v_exp_f32_e32 v87, v87
	ds_read_b64_tr_b16 v[212:213], v204 offset:12928
	s_waitcnt lgkmcnt(6)
	v_mfma_f32_32x32x16_bf16 v[2:17], v[214:217], v[218:221], v[2:17]
	ds_read_b64_tr_b16 v[214:215], v204 offset:10432
	v_exp_f32_e32 v88, v88
	v_exp_f32_e32 v89, v89
	ds_read_b64_tr_b16 v[216:217], v204 offset:12992
	s_waitcnt lgkmcnt(6)
	v_cvt_pk_bf16_f32 v218, v82, v83
	v_cvt_pk_bf16_f32 v219, v84, v85
	v_cvt_pk_bf16_f32 v220, v86, v87
	v_cvt_pk_bf16_f32 v221, v88, v89
	s_nop 1
	v_mfma_f32_32x32x16_bf16 v[50:65], v[198:201], v[218:221], v[50:65]
	ds_read_b64_tr_b16 v[198:199], v204 offset:15360
	ds_read_b64_tr_b16 v[200:201], v204 offset:17920
	s_waitcnt lgkmcnt(6)
	v_mfma_f32_32x32x16_bf16 v[34:49], v[206:209], v[218:221], v[34:49]
	ds_read_b64_tr_b16 v[206:207], v204 offset:15424
	ds_read_b64_tr_b16 v[208:209], v204 offset:17984
	s_waitcnt lgkmcnt(6)
	v_mfma_f32_32x32x16_bf16 v[18:33], v[210:213], v[218:221], v[18:33]
	ds_read_b64_tr_b16 v[210:211], v204 offset:15488
	ds_read_b64_tr_b16 v[212:213], v204 offset:18048
	s_waitcnt lgkmcnt(6)
	v_mfma_f32_32x32x16_bf16 v[2:17], v[214:217], v[218:221], v[2:17]
	ds_read_b64_tr_b16 v[214:215], v204 offset:15552
	v_exp_f32_e32 v90, v90
	v_exp_f32_e32 v91, v91
	v_exp_f32_e32 v92, v92
	v_exp_f32_e32 v93, v93
	v_exp_f32_e32 v94, v94
	v_exp_f32_e32 v95, v95
	v_exp_f32_e32 v96, v96
	v_exp_f32_e32 v97, v97
	ds_read_b64_tr_b16 v[216:217], v204 offset:18112
	s_waitcnt lgkmcnt(0)
	v_cvt_pk_bf16_f32 v218, v90, v91
	v_cvt_pk_bf16_f32 v219, v92, v93
	v_cvt_pk_bf16_f32 v220, v94, v95
	v_cvt_pk_bf16_f32 v221, v96, v97
	s_nop 1
	v_mfma_f32_32x32x16_bf16 v[50:65], v[198:201], v[218:221], v[50:65]
	s_cmpk_gt_u32 s12, 0x41
	s_barrier
	v_mfma_f32_32x32x16_bf16 v[34:49], v[206:209], v[218:221], v[34:49]
	v_mfma_f32_32x32x16_bf16 v[18:33], v[210:213], v[218:221], v[18:33]
	v_mfma_f32_32x32x16_bf16 v[2:17], v[214:217], v[218:221], v[2:17]
	s_cbranch_scc1 .LBB0_602
	s_mul_i32 s0, s11, 0x9400
	s_add_i32 s0, s0, 0
	v_add3_u32 v198, s0, v187, v188
	s_waitcnt vmcnt(0)
	ds_write_b128 v198, v[146:149]
	v_add3_u32 v198, s0, v189, v190
	ds_write_b128 v198, v[150:153]
	v_add3_u32 v198, s0, v191, v188
	ds_write_b128 v198, v[154:157] offset:17408
	v_add3_u32 v198, s0, v192, v190
	s_cmp_gt_u32 s12, 63
	ds_write_b128 v198, v[158:161] offset:17408
	s_cbranch_scc1 .LBB0_602
	global_load_dwordx4 v[146:149], v[174:175], off
	global_load_dwordx4 v[150:153], v[176:177], off
	global_load_dwordx4 v[154:157], v[178:179], off
	global_load_dwordx4 v[158:161], v[180:181], off
	s_mov_b32 s0, s101
	s_mov_b32 s1, 0
	v_lshl_add_u64 v[174:175], s[0:1], 0, v[174:175]
	v_lshl_add_u64 v[176:177], s[0:1], 0, v[176:177]
	v_lshl_add_u64 v[178:179], s[0:1], 0, v[178:179]
	v_lshl_add_u64 v[180:181], s[0:1], 0, v[180:181]

; __global__ void __launch_bounds__(512, 2) mega_fwd(Params p) {
;     extern __shared__ __attribute__((aligned(16))) unsigned char lds[];
	.amdhsa_kernel _Z8mega_fwd6Params
		.amdhsa_group_segment_fixed_size 0
		.amdhsa_private_segment_fixed_size 0
		.amdhsa_kernarg_size 488
		.amdhsa_user_sgpr_count 2
		.amdhsa_user_sgpr_dispatch_ptr 0
		.amdhsa_user_sgpr_queue_ptr 0
		.amdhsa_user_sgpr_kernarg_segment_ptr 1
		.amdhsa_user_sgpr_dispatch_id 0
		.amdhsa_user_sgpr_kernarg_preload_length 0
		.amdhsa_user_sgpr_kernarg_preload_offset 0
		.amdhsa_user_sgpr_private_segment_size 0
		.amdhsa_uses_dynamic_stack 0
		.amdhsa_enable_private_segment 0
		.amdhsa_system_sgpr_workgroup_id_x 1
		.amdhsa_system_sgpr_workgroup_id_y 0
		.amdhsa_system_sgpr_workgroup_id_z 0
		.amdhsa_system_sgpr_workgroup_info 0
		.amdhsa_system_vgpr_workitem_id 2
		.amdhsa_next_free_vgpr 256
		.amdhsa_next_free_sgpr 102
		.amdhsa_accum_offset 256
		.amdhsa_reserve_vcc 1
		.amdhsa_float_round_mode_32 0
		.amdhsa_float_round_mode_16_64 0
		.amdhsa_float_denorm_mode_32 3
		.amdhsa_float_denorm_mode_16_64 3
		.amdhsa_dx10_clamp 1
		.amdhsa_ieee_mode 1
		.amdhsa_fp16_overflow 0
		.amdhsa_tg_split 0
		.amdhsa_exception_fp_ieee_invalid_op 0
		.amdhsa_exception_fp_denorm_src 0
		.amdhsa_exception_fp_ieee_div_zero 0
		.amdhsa_exception_fp_ieee_overflow 0
		.amdhsa_exception_fp_ieee_underflow 0
		.amdhsa_exception_fp_ieee_inexact 0
		.amdhsa_exception_int_div_zero 0
	.end_amdhsa_kernel

; __global__ void __launch_bounds__(512, 2) mega_fwd(Params p) {
;     extern __shared__ __attribute__((aligned(16))) unsigned char lds[];
amdhsa.kernels:
  - .agpr_count:     0
    .args:
      - .offset:         0
        .size:           232
        .value_kind:     by_value
      - .offset:         232
        .size:           4
        .value_kind:     hidden_block_count_x
      - .offset:         236
        .size:           4
        .value_kind:     hidden_block_count_y
      - .offset:         240
        .size:           4
        .value_kind:     hidden_block_count_z
      - .offset:         244
        .size:           2
        .value_kind:     hidden_group_size_x
      - .offset:         246
        .size:           2
        .value_kind:     hidden_group_size_y
      - .offset:         248
        .size:           2
        .value_kind:     hidden_group_size_z
      - .offset:         250
        .size:           2
        .value_kind:     hidden_remainder_x
      - .offset:         252
        .size:           2
        .value_kind:     hidden_remainder_y
      - .offset:         254
        .size:           2
        .value_kind:     hidden_remainder_z
      - .offset:         272
        .size:           8
        .value_kind:     hidden_global_offset_x
      - .offset:         280
        .size:           8
        .value_kind:     hidden_global_offset_y
      - .offset:         288
        .size:           8
        .value_kind:     hidden_global_offset_z
      - .offset:         296
        .size:           2
        .value_kind:     hidden_grid_dims
      - .offset:         320
        .size:           8
        .value_kind:     hidden_multigrid_sync_arg
      - .offset:         352
        .size:           4
        .value_kind:     hidden_dynamic_lds_size
    .group_segment_fixed_size: 0
    .kernarg_segment_align: 8
    .kernarg_segment_size: 488
    .language:       OpenCL C
    .language_version:
      - 2
      - 0
    .max_flat_workgroup_size: 512
    .name:           _Z8mega_fwd6Params
    .private_segment_fixed_size: 0
    .sgpr_count:     108
    .sgpr_spill_count: 412
    .symbol:         _Z8mega_fwd6Params.kd
    .uniform_work_group_size: 1
    .uses_dynamic_stack: false
    .vgpr_count:     256
    .vgpr_spill_count: 0
    .wavefront_size: 64
